# L3a GEMM: branch-gate units (48 valid columns, all in the bj=0 half) skip the bj=1 MFMA groups
# speedup vs baseline: 1.0062x; 1.0062x over previous
.LBB0_892:
	s_add_u32 s18, s16, 0xfff80080
	s_addc_u32 s19, s17, -1
	s_add_i32 s22, 0, 0x10000
	v_add_u32_e32 v32, s22, v150
	ds_read_b128 v[130:133], v32
	ds_read_b128 v[152:155], v32 offset:1024
	ds_read_b128 v[156:159], v32 offset:2048
	ds_read_b128 v[160:163], v32 offset:3072
	s_cmp_eq_u32 s15, 28
	s_cselect_b32 s21, s5, s19
	s_cselect_b32 s20, s4, s18
	s_cselect_b32 s19, s13, s11
	s_cselect_b32 s18, s12, s9
	v_lshl_add_u64 v[148:149], s[16:17], 0, v[144:145]
	s_add_i32 m0, s30, 0xc000
	ds_read_b128 v[164:167], v151
	ds_read_b128 v[168:171], v151 offset:1024
	ds_read_b128 v[172:175], v151 offset:2048
	ds_read_b128 v[180:183], v151 offset:3072
	ds_read_b128 v[184:187], v151 offset:4096
	ds_read_b128 v[188:191], v151 offset:5120
	ds_read_b128 v[192:195], v151 offset:6144
	ds_read_b128 v[196:199], v151 offset:7168
	global_load_lds_dwordx4 v[148:149], off
	v_lshl_add_u64 v[148:149], s[16:17], 0, v[146:147]
	s_add_i32 m0, s30, 0xe000
	s_nop 0
	global_load_lds_dwordx4 v[148:149], off
	s_waitcnt lgkmcnt(8)
	s_barrier
	s_waitcnt lgkmcnt(0)
	s_setprio 1
	s_waitcnt lgkmcnt(0)
	v_mfma_f32_16x16x32_bf16 v[126:129], v[130:133], v[164:167], v[126:129]
	v_mfma_f32_16x16x32_bf16 v[122:125], v[156:159], v[164:167], v[122:125]
	v_mfma_f32_16x16x32_bf16 v[118:121], v[130:133], v[172:175], v[118:121]
	v_mfma_f32_16x16x32_bf16 v[114:117], v[156:159], v[172:175], v[114:117]
	v_mfma_f32_16x16x32_bf16 v[106:109], v[130:133], v[184:187], v[106:109]
	v_mfma_f32_16x16x32_bf16 v[98:101], v[156:159], v[184:187], v[98:101]
	v_mfma_f32_16x16x32_bf16 v[90:93], v[130:133], v[192:195], v[90:93]
	v_mfma_f32_16x16x32_bf16 v[82:85], v[156:159], v[192:195], v[82:85]
	v_mfma_f32_16x16x32_bf16 v[126:129], v[152:155], v[168:171], v[126:129]
	v_mfma_f32_16x16x32_bf16 v[122:125], v[160:163], v[168:171], v[122:125]
	v_mfma_f32_16x16x32_bf16 v[118:121], v[152:155], v[180:183], v[118:121]
	v_mfma_f32_16x16x32_bf16 v[114:117], v[160:163], v[180:183], v[114:117]
	v_mfma_f32_16x16x32_bf16 v[106:109], v[152:155], v[188:191], v[106:109]
	v_mfma_f32_16x16x32_bf16 v[98:101], v[160:163], v[188:191], v[98:101]
	v_mfma_f32_16x16x32_bf16 v[90:93], v[152:155], v[196:199], v[90:93]
	v_mfma_f32_16x16x32_bf16 v[82:85], v[160:163], v[196:199], v[82:85]
	s_setprio 0
	s_barrier
	s_add_i32 s40, 0, 0x14000
	s_add_i32 s22, s22, s29
	v_add_u32_e32 v32, s40, v150
	v_lshl_add_u64 v[148:149], s[18:19], 0, v[138:139]
	s_mov_b32 m0, s22
	ds_read_b128 v[200:203], v32
	ds_read_b128 v[204:207], v32 offset:1024
	ds_read_b128 v[208:211], v32 offset:2048
	ds_read_b128 v[212:215], v32 offset:3072
	global_load_lds_dwordx4 v[148:149], off
	v_lshl_add_u64 v[176:177], s[18:19], 0, v[134:135]
	s_add_i32 m0, s22, 0x2000
	s_nop 0
	global_load_lds_dwordx4 v[176:177], off
	s_barrier
	s_waitcnt lgkmcnt(0)
	s_setprio 1
	s_waitcnt lgkmcnt(0)
	s_cmp_eq_u32 s14, 2
	s_cbranch_scc1 .Ll3a_skip2
	v_mfma_f32_16x16x32_bf16 v[110:113], v[200:203], v[164:167], v[110:113]
	v_mfma_f32_16x16x32_bf16 v[102:105], v[208:211], v[164:167], v[102:105]
	v_mfma_f32_16x16x32_bf16 v[94:97], v[200:203], v[172:175], v[94:97]
	v_mfma_f32_16x16x32_bf16 v[86:89], v[208:211], v[172:175], v[86:89]
	v_mfma_f32_16x16x32_bf16 v[78:81], v[200:203], v[184:187], v[78:81]
	v_mfma_f32_16x16x32_bf16 v[74:77], v[208:211], v[184:187], v[74:77]
	v_mfma_f32_16x16x32_bf16 v[70:73], v[200:203], v[192:195], v[70:73]
	v_mfma_f32_16x16x32_bf16 v[66:69], v[208:211], v[192:195], v[66:69]
	v_mfma_f32_16x16x32_bf16 v[110:113], v[204:207], v[168:171], v[110:113]
	v_mfma_f32_16x16x32_bf16 v[102:105], v[212:215], v[168:171], v[102:105]
	v_mfma_f32_16x16x32_bf16 v[94:97], v[204:207], v[180:183], v[94:97]
	v_mfma_f32_16x16x32_bf16 v[86:89], v[212:215], v[180:183], v[86:89]
	v_mfma_f32_16x16x32_bf16 v[78:81], v[204:207], v[188:191], v[78:81]
	v_mfma_f32_16x16x32_bf16 v[74:77], v[212:215], v[188:191], v[74:77]
	v_mfma_f32_16x16x32_bf16 v[70:73], v[204:207], v[196:199], v[70:73]
	v_mfma_f32_16x16x32_bf16 v[66:69], v[212:215], v[196:199], v[66:69]
.Ll3a_skip2:
	s_setprio 0
	s_mov_b32 m0, s30
	v_lshl_add_u64 v[216:217], s[20:21], 0, v[140:141]
	s_barrier
	ds_read_b128 v[164:167], v151 offset:16384
	ds_read_b128 v[168:171], v151 offset:17408
	ds_read_b128 v[172:175], v151 offset:18432
	ds_read_b128 v[180:183], v151 offset:19456
	ds_read_b128 v[184:187], v151 offset:20480
	ds_read_b128 v[188:191], v151 offset:21504
	ds_read_b128 v[192:195], v151 offset:22528
	ds_read_b128 v[196:199], v151 offset:23552
	global_load_lds_dwordx4 v[216:217], off
	v_lshl_add_u64 v[218:219], s[20:21], 0, v[136:137]
	s_mov_b32 m0, s31
	s_nop 0
	global_load_lds_dwordx4 v[218:219], off
	s_barrier
	s_waitcnt lgkmcnt(0)
	s_setprio 1
	s_waitcnt lgkmcnt(0)
	v_mfma_f32_16x16x32_bf16 v[62:65], v[130:133], v[164:167], v[62:65]
	v_mfma_f32_16x16x32_bf16 v[58:61], v[156:159], v[164:167], v[58:61]
	v_mfma_f32_16x16x32_bf16 v[54:57], v[130:133], v[172:175], v[54:57]
	v_mfma_f32_16x16x32_bf16 v[50:53], v[156:159], v[172:175], v[50:53]
	v_mfma_f32_16x16x32_bf16 v[42:45], v[130:133], v[184:187], v[42:45]
	v_mfma_f32_16x16x32_bf16 v[34:37], v[156:159], v[184:187], v[34:37]
	v_mfma_f32_16x16x32_bf16 v[24:27], v[130:133], v[192:195], v[24:27]
	v_mfma_f32_16x16x32_bf16 v[16:19], v[156:159], v[192:195], v[16:19]
	v_mfma_f32_16x16x32_bf16 v[62:65], v[152:155], v[168:171], v[62:65]
	v_mfma_f32_16x16x32_bf16 v[58:61], v[160:163], v[168:171], v[58:61]
	v_mfma_f32_16x16x32_bf16 v[54:57], v[152:155], v[180:183], v[54:57]
	v_mfma_f32_16x16x32_bf16 v[50:53], v[160:163], v[180:183], v[50:53]
	v_mfma_f32_16x16x32_bf16 v[42:45], v[152:155], v[188:191], v[42:45]
	v_mfma_f32_16x16x32_bf16 v[34:37], v[160:163], v[188:191], v[34:37]
	v_mfma_f32_16x16x32_bf16 v[24:27], v[152:155], v[196:199], v[24:27]
	v_mfma_f32_16x16x32_bf16 v[16:19], v[160:163], v[196:199], v[16:19]
	s_setprio 0
	s_barrier
	s_add_u32 s22, s18, 0x80000
	s_addc_u32 s23, s19, 0
	s_add_i32 s40, s40, s29
	v_lshl_add_u64 v[130:131], s[22:23], 0, v[138:139]
	s_mov_b32 m0, s40
	s_nop 0
	global_load_lds_dwordx4 v[130:131], off
	v_lshl_add_u64 v[130:131], s[22:23], 0, v[134:135]
	s_add_i32 m0, s40, 0x2000
	s_nop 0
	global_load_lds_dwordx4 v[130:131], off
	s_waitcnt vmcnt(6)
	s_barrier
	s_setprio 1
	s_cmp_eq_u32 s14, 2
	s_cbranch_scc1 .Ll3a_skip4
	v_mfma_f32_16x16x32_bf16 v[46:49], v[200:203], v[164:167], v[46:49]
	v_mfma_f32_16x16x32_bf16 v[38:41], v[208:211], v[164:167], v[38:41]
	v_mfma_f32_16x16x32_bf16 v[28:31], v[200:203], v[172:175], v[28:31]
	v_mfma_f32_16x16x32_bf16 v[20:23], v[208:211], v[172:175], v[20:23]
	v_mfma_f32_16x16x32_bf16 v[12:15], v[200:203], v[184:187], v[12:15]
	v_mfma_f32_16x16x32_bf16 v[8:11], v[208:211], v[184:187], v[8:11]
	v_mfma_f32_16x16x32_bf16 v[4:7], v[200:203], v[192:195], v[4:7]
	v_mfma_f32_16x16x32_bf16 v[0:3], v[208:211], v[192:195], v[0:3]
	v_mfma_f32_16x16x32_bf16 v[46:49], v[204:207], v[168:171], v[46:49]
	v_mfma_f32_16x16x32_bf16 v[38:41], v[212:215], v[168:171], v[38:41]
	v_mfma_f32_16x16x32_bf16 v[28:31], v[204:207], v[180:183], v[28:31]
	v_mfma_f32_16x16x32_bf16 v[20:23], v[212:215], v[180:183], v[20:23]
	v_mfma_f32_16x16x32_bf16 v[12:15], v[204:207], v[188:191], v[12:15]
	v_mfma_f32_16x16x32_bf16 v[8:11], v[212:215], v[188:191], v[8:11]
	v_mfma_f32_16x16x32_bf16 v[4:7], v[204:207], v[196:199], v[4:7]
	v_mfma_f32_16x16x32_bf16 v[0:3], v[212:215], v[196:199], v[0:3]
.Ll3a_skip4:
	s_setprio 0
	s_add_i32 s22, 0, 0x18000
	v_add_u32_e32 v32, s22, v150
	s_barrier
	ds_read_b128 v[130:133], v32
	ds_read_b128 v[152:155], v32 offset:1024
	ds_read_b128 v[156:159], v32 offset:2048
	ds_read_b128 v[160:163], v32 offset:3072
	s_add_u32 s20, s20, 0x80000
	s_addc_u32 s21, s21, 0
	s_mov_b32 m0, s34
	v_lshl_add_u64 v[200:201], s[20:21], 0, v[140:141]
	ds_read_b128 v[164:167], v151 offset:32768
	ds_read_b128 v[168:171], v151 offset:33792
	ds_read_b128 v[172:175], v151 offset:34816
	ds_read_b128 v[180:183], v151 offset:35840
	ds_read_b128 v[184:187], v151 offset:36864
	ds_read_b128 v[188:191], v151 offset:37888
	ds_read_b128 v[192:195], v151 offset:38912
	ds_read_b128 v[196:199], v151 offset:39936
	global_load_lds_dwordx4 v[200:201], off
	v_lshl_add_u64 v[200:201], s[20:21], 0, v[136:137]
	s_mov_b32 m0, s35
	s_nop 0
	global_load_lds_dwordx4 v[200:201], off
	s_waitcnt lgkmcnt(8)
	s_barrier
	s_waitcnt lgkmcnt(0)
	s_setprio 1
	s_waitcnt lgkmcnt(0)
	v_mfma_f32_16x16x32_bf16 v[126:129], v[130:133], v[164:167], v[126:129]
	v_mfma_f32_16x16x32_bf16 v[122:125], v[156:159], v[164:167], v[122:125]
	v_mfma_f32_16x16x32_bf16 v[118:121], v[130:133], v[172:175], v[118:121]
	v_mfma_f32_16x16x32_bf16 v[114:117], v[156:159], v[172:175], v[114:117]
	v_mfma_f32_16x16x32_bf16 v[106:109], v[130:133], v[184:187], v[106:109]
	v_mfma_f32_16x16x32_bf16 v[98:101], v[156:159], v[184:187], v[98:101]
	v_mfma_f32_16x16x32_bf16 v[90:93], v[130:133], v[192:195], v[90:93]
	v_mfma_f32_16x16x32_bf16 v[82:85], v[156:159], v[192:195], v[82:85]
	v_mfma_f32_16x16x32_bf16 v[126:129], v[152:155], v[168:171], v[126:129]
	v_mfma_f32_16x16x32_bf16 v[122:125], v[160:163], v[168:171], v[122:125]
	v_mfma_f32_16x16x32_bf16 v[118:121], v[152:155], v[180:183], v[118:121]
	v_mfma_f32_16x16x32_bf16 v[114:117], v[160:163], v[180:183], v[114:117]
	v_mfma_f32_16x16x32_bf16 v[106:109], v[152:155], v[188:191], v[106:109]
	v_mfma_f32_16x16x32_bf16 v[98:101], v[160:163], v[188:191], v[98:101]
	v_mfma_f32_16x16x32_bf16 v[90:93], v[152:155], v[196:199], v[90:93]
	v_mfma_f32_16x16x32_bf16 v[82:85], v[160:163], v[196:199], v[82:85]
	s_setprio 0
	s_barrier
	s_add_i32 s20, 0, 0x1c000
	s_add_i32 s21, s22, s29
	v_add_u32_e32 v32, s20, v150
	v_lshl_add_u64 v[148:149], v[148:149], 0, s[88:89]
	s_mov_b32 m0, s21
	ds_read_b128 v[200:203], v32
	ds_read_b128 v[204:207], v32 offset:1024
	ds_read_b128 v[208:211], v32 offset:2048
	ds_read_b128 v[212:215], v32 offset:3072
	global_load_lds_dwordx4 v[148:149], off
	v_lshl_add_u64 v[148:149], v[176:177], 0, s[88:89]
	s_add_i32 m0, s21, 0x2000
	s_nop 0
	global_load_lds_dwordx4 v[148:149], off
	s_barrier
	s_waitcnt lgkmcnt(0)
	s_setprio 1
	s_waitcnt lgkmcnt(0)
	s_cmp_eq_u32 s14, 2
	s_cbranch_scc1 .Ll3a_skip6
	v_mfma_f32_16x16x32_bf16 v[110:113], v[200:203], v[164:167], v[110:113]
	v_mfma_f32_16x16x32_bf16 v[102:105], v[208:211], v[164:167], v[102:105]
	v_mfma_f32_16x16x32_bf16 v[94:97], v[200:203], v[172:175], v[94:97]
	v_mfma_f32_16x16x32_bf16 v[86:89], v[208:211], v[172:175], v[86:89]
	v_mfma_f32_16x16x32_bf16 v[78:81], v[200:203], v[184:187], v[78:81]
	v_mfma_f32_16x16x32_bf16 v[74:77], v[208:211], v[184:187], v[74:77]
	v_mfma_f32_16x16x32_bf16 v[70:73], v[200:203], v[192:195], v[70:73]
	v_mfma_f32_16x16x32_bf16 v[66:69], v[208:211], v[192:195], v[66:69]
	v_mfma_f32_16x16x32_bf16 v[110:113], v[204:207], v[168:171], v[110:113]
	v_mfma_f32_16x16x32_bf16 v[102:105], v[212:215], v[168:171], v[102:105]
	v_mfma_f32_16x16x32_bf16 v[94:97], v[204:207], v[180:183], v[94:97]
	v_mfma_f32_16x16x32_bf16 v[86:89], v[212:215], v[180:183], v[86:89]
	v_mfma_f32_16x16x32_bf16 v[78:81], v[204:207], v[188:191], v[78:81]
	v_mfma_f32_16x16x32_bf16 v[74:77], v[212:215], v[188:191], v[74:77]
	v_mfma_f32_16x16x32_bf16 v[70:73], v[204:207], v[196:199], v[70:73]
	v_mfma_f32_16x16x32_bf16 v[66:69], v[212:215], v[196:199], v[66:69]
.Ll3a_skip6:
	s_setprio 0
	s_mov_b32 m0, s36
	v_lshl_add_u64 v[148:149], v[216:217], 0, s[88:89]
	s_barrier
	ds_read_b128 v[164:167], v151 offset:49152
	ds_read_b128 v[168:171], v151 offset:50176
	ds_read_b128 v[172:175], v151 offset:51200
	ds_read_b128 v[180:183], v151 offset:52224
	ds_read_b128 v[184:187], v151 offset:53248
	ds_read_b128 v[188:191], v151 offset:54272
	ds_read_b128 v[192:195], v151 offset:55296
	ds_read_b128 v[196:199], v151 offset:56320
	global_load_lds_dwordx4 v[148:149], off
	v_lshl_add_u64 v[148:149], v[218:219], 0, s[88:89]
	s_mov_b32 m0, s37
	s_nop 0
	global_load_lds_dwordx4 v[148:149], off
	s_barrier
	s_waitcnt lgkmcnt(0)
	s_setprio 1
	s_waitcnt lgkmcnt(0)
	v_mfma_f32_16x16x32_bf16 v[62:65], v[130:133], v[164:167], v[62:65]
	v_mfma_f32_16x16x32_bf16 v[58:61], v[156:159], v[164:167], v[58:61]
	v_mfma_f32_16x16x32_bf16 v[54:57], v[130:133], v[172:175], v[54:57]
	v_mfma_f32_16x16x32_bf16 v[50:53], v[156:159], v[172:175], v[50:53]
	v_mfma_f32_16x16x32_bf16 v[42:45], v[130:133], v[184:187], v[42:45]
	v_mfma_f32_16x16x32_bf16 v[34:37], v[156:159], v[184:187], v[34:37]
	v_mfma_f32_16x16x32_bf16 v[24:27], v[130:133], v[192:195], v[24:27]
	v_mfma_f32_16x16x32_bf16 v[16:19], v[156:159], v[192:195], v[16:19]
	v_mfma_f32_16x16x32_bf16 v[62:65], v[152:155], v[168:171], v[62:65]
	v_mfma_f32_16x16x32_bf16 v[58:61], v[160:163], v[168:171], v[58:61]
	v_mfma_f32_16x16x32_bf16 v[54:57], v[152:155], v[180:183], v[54:57]
	v_mfma_f32_16x16x32_bf16 v[50:53], v[160:163], v[180:183], v[50:53]
	v_mfma_f32_16x16x32_bf16 v[42:45], v[152:155], v[188:191], v[42:45]
	v_mfma_f32_16x16x32_bf16 v[34:37], v[160:163], v[188:191], v[34:37]
	v_mfma_f32_16x16x32_bf16 v[24:27], v[152:155], v[196:199], v[24:27]
	v_mfma_f32_16x16x32_bf16 v[16:19], v[160:163], v[196:199], v[16:19]
	s_setprio 0
	s_barrier
	s_add_u32 s18, s18, 0x80080
	s_addc_u32 s19, s19, 0
	s_add_i32 s20, s20, s29
	v_lshl_add_u64 v[130:131], s[18:19], 0, v[138:139]
	s_mov_b32 m0, s20
	s_nop 0
	global_load_lds_dwordx4 v[130:131], off
	v_lshl_add_u64 v[130:131], s[18:19], 0, v[134:135]
	s_add_i32 m0, s20, 0x2000
	s_nop 0
	global_load_lds_dwordx4 v[130:131], off
	s_waitcnt vmcnt(6)
	s_barrier
	s_setprio 1
	s_cmp_eq_u32 s14, 2
	s_cbranch_scc1 .Ll3a_skip8
	v_mfma_f32_16x16x32_bf16 v[46:49], v[200:203], v[164:167], v[46:49]
	v_mfma_f32_16x16x32_bf16 v[38:41], v[208:211], v[164:167], v[38:41]
	v_mfma_f32_16x16x32_bf16 v[28:31], v[200:203], v[172:175], v[28:31]
	v_mfma_f32_16x16x32_bf16 v[20:23], v[208:211], v[172:175], v[20:23]
	v_mfma_f32_16x16x32_bf16 v[12:15], v[200:203], v[184:187], v[12:15]
	v_mfma_f32_16x16x32_bf16 v[8:11], v[208:211], v[184:187], v[8:11]
	v_mfma_f32_16x16x32_bf16 v[4:7], v[200:203], v[192:195], v[4:7]
	v_mfma_f32_16x16x32_bf16 v[0:3], v[208:211], v[192:195], v[0:3]
	v_mfma_f32_16x16x32_bf16 v[46:49], v[204:207], v[168:171], v[46:49]
	v_mfma_f32_16x16x32_bf16 v[38:41], v[212:215], v[168:171], v[38:41]
	v_mfma_f32_16x16x32_bf16 v[28:31], v[204:207], v[180:183], v[28:31]
	v_mfma_f32_16x16x32_bf16 v[20:23], v[212:215], v[180:183], v[20:23]
	v_mfma_f32_16x16x32_bf16 v[12:15], v[204:207], v[188:191], v[12:15]
	v_mfma_f32_16x16x32_bf16 v[8:11], v[212:215], v[188:191], v[8:11]
	v_mfma_f32_16x16x32_bf16 v[4:7], v[204:207], v[196:199], v[4:7]
	v_mfma_f32_16x16x32_bf16 v[0:3], v[212:215], v[196:199], v[0:3]
.Ll3a_skip8:
	s_setprio 0
	s_add_i32 s15, s15, 2
	s_add_u32 s16, s16, 0x100
	s_addc_u32 s17, s17, 0
	s_add_u32 s9, s9, 0x100
	s_addc_u32 s11, s11, 0
	s_cmp_gt_u32 s15, 29
	s_barrier
	s_cbranch_scc0 .LBB0_892
	s_mov_b64 s[16:17], 0
	s_add_u32 s16, s76, s16
	s_addc_u32 s17, s77, s17
	s_cmp_gt_i32 s14, 1
	s_cbranch_scc0 .LBB0_897
	s_mov_b64 s[18:19], 0
	s_mov_b64 s[22:23], 0
	s_and_saveexec_b64 s[20:21], s[2:3]
	s_xor_b64 s[20:21], exec, s[20:21]
	s_cbranch_execz .LBB0_896
	v_lshlrev_b32_e32 v32, 2, v142
	v_lshl_add_u64 v[130:131], s[16:17], 0, v[32:33]
	v_mul_f32_e32 v32, 0xbfb8aa3b, v126
	v_exp_f32_e32 v32, v32
	s_mov_b64 s[22:23], 0x11341000
	v_lshl_add_u64 v[148:149], v[130:131], 0, s[22:23]
	v_lshl_add_u32 v158, s39, 8, v143
	v_add_f32_e32 v32, 1.0, v32
	v_rcp_f32_e32 v130, v32
	v_mul_f32_e32 v32, 0xbfb8aa3b, v122
	v_exp_f32_e32 v32, v32
	v_mad_i64_i32 v[156:157], s[22:23], v158, s50, v[148:149]
	v_add_f32_e32 v32, 1.0, v32
	v_rcp_f32_e32 v152, v32
	v_mul_f32_e32 v32, 0xbfb8aa3b, v127
	v_exp_f32_e32 v32, v32
	s_nop 0
	v_add_f32_e32 v32, 1.0, v32
	v_rcp_f32_e32 v131, v32
	v_mul_f32_e32 v32, 0xbfb8aa3b, v123
	v_exp_f32_e32 v32, v32
	s_nop 0
	v_add_f32_e32 v32, 1.0, v32
	v_rcp_f32_e32 v153, v32
	v_mul_f32_e32 v32, 0xbfb8aa3b, v128
	v_exp_f32_e32 v32, v32
	s_nop 0
	v_add_f32_e32 v32, 1.0, v32
	v_rcp_f32_e32 v132, v32
	v_mul_f32_e32 v32, 0xbfb8aa3b, v124
	v_exp_f32_e32 v32, v32
	s_nop 0
	v_add_f32_e32 v32, 1.0, v32
	v_rcp_f32_e32 v154, v32
	v_mul_f32_e32 v32, 0xbfb8aa3b, v129
	v_exp_f32_e32 v32, v32
	s_nop 0
	v_add_f32_e32 v32, 1.0, v32
	v_rcp_f32_e32 v133, v32
	v_mul_f32_e32 v32, 0xbfb8aa3b, v125
	v_exp_f32_e32 v32, v32
	s_nop 0
	v_add_f32_e32 v32, 1.0, v32
	v_rcp_f32_e32 v155, v32
	v_mul_f32_e32 v32, 0xbfb8aa3b, v118
	v_exp_f32_e32 v32, v32
	global_store_dwordx4 v[156:157], v[130:133], off
	global_store_dwordx4 v[156:157], v[152:155], off offset:16
	v_add_f32_e32 v32, 1.0, v32
	v_rcp_f32_e32 v130, v32
	v_mul_f32_e32 v32, 0xbfb8aa3b, v114
	v_exp_f32_e32 v32, v32
	s_nop 0
	v_add_f32_e32 v32, 1.0, v32
	v_rcp_f32_e32 v152, v32
	v_mul_f32_e32 v32, 0xbfb8aa3b, v119
	v_exp_f32_e32 v32, v32
	s_nop 0
	v_add_f32_e32 v32, 1.0, v32
	v_rcp_f32_e32 v131, v32
	v_mul_f32_e32 v32, 0xbfb8aa3b, v115
	v_exp_f32_e32 v32, v32
	s_nop 0
	v_add_f32_e32 v32, 1.0, v32
	v_rcp_f32_e32 v153, v32
	v_mul_f32_e32 v32, 0xbfb8aa3b, v120
	v_exp_f32_e32 v32, v32
	s_nop 0
	v_add_f32_e32 v32, 1.0, v32
	v_rcp_f32_e32 v132, v32
	v_mul_f32_e32 v32, 0xbfb8aa3b, v116
	v_exp_f32_e32 v32, v32
	s_nop 0
	v_add_f32_e32 v32, 1.0, v32
	v_rcp_f32_e32 v154, v32
	v_mul_f32_e32 v32, 0xbfb8aa3b, v121
	v_exp_f32_e32 v32, v32
	s_nop 0
	v_add_f32_e32 v32, 1.0, v32
	v_rcp_f32_e32 v133, v32
	v_mul_f32_e32 v32, 0xbfb8aa3b, v117
	v_exp_f32_e32 v32, v32
	s_nop 0
	v_add_f32_e32 v32, 1.0, v32
	v_rcp_f32_e32 v155, v32
	v_or_b32_e32 v32, 16, v158
	v_mad_i64_i32 v[156:157], s[22:23], v32, s50, v[148:149]
	v_mul_f32_e32 v32, 0xbfb8aa3b, v106
	v_exp_f32_e32 v32, v32
	global_store_dwordx4 v[156:157], v[130:133], off
	global_store_dwordx4 v[156:157], v[152:155], off offset:16
	v_add_f32_e32 v32, 1.0, v32
	v_rcp_f32_e32 v130, v32
	v_mul_f32_e32 v32, 0xbfb8aa3b, v98
	v_exp_f32_e32 v32, v32
	s_nop 0
	v_add_f32_e32 v32, 1.0, v32
	v_rcp_f32_e32 v152, v32
	v_mul_f32_e32 v32, 0xbfb8aa3b, v107
	v_exp_f32_e32 v32, v32
	s_nop 0
	v_add_f32_e32 v32, 1.0, v32
	v_rcp_f32_e32 v131, v32
	v_mul_f32_e32 v32, 0xbfb8aa3b, v99
	v_exp_f32_e32 v32, v32
	s_nop 0
	v_add_f32_e32 v32, 1.0, v32
	v_rcp_f32_e32 v153, v32
	v_mul_f32_e32 v32, 0xbfb8aa3b, v108
	v_exp_f32_e32 v32, v32
	s_nop 0
	v_add_f32_e32 v32, 1.0, v32
	v_rcp_f32_e32 v132, v32
	v_mul_f32_e32 v32, 0xbfb8aa3b, v100
	v_exp_f32_e32 v32, v32
	s_nop 0
	v_add_f32_e32 v32, 1.0, v32
	v_rcp_f32_e32 v154, v32
	v_mul_f32_e32 v32, 0xbfb8aa3b, v109
	v_exp_f32_e32 v32, v32
	s_nop 0
	v_add_f32_e32 v32, 1.0, v32
	v_rcp_f32_e32 v133, v32
	v_mul_f32_e32 v32, 0xbfb8aa3b, v101
	v_exp_f32_e32 v32, v32
	s_nop 0
	v_add_f32_e32 v32, 1.0, v32
	v_rcp_f32_e32 v155, v32
	v_or_b32_e32 v32, 32, v158
	v_mad_i64_i32 v[156:157], s[22:23], v32, s50, v[148:149]
	v_mul_f32_e32 v32, 0xbfb8aa3b, v90
	v_exp_f32_e32 v32, v32
	global_store_dwordx4 v[156:157], v[130:133], off
	global_store_dwordx4 v[156:157], v[152:155], off offset:16
	v_add_f32_e32 v32, 1.0, v32
	v_rcp_f32_e32 v130, v32
	v_mul_f32_e32 v32, 0xbfb8aa3b, v82
	v_exp_f32_e32 v32, v32
	s_nop 0
	v_add_f32_e32 v32, 1.0, v32
	v_rcp_f32_e32 v152, v32
	v_mul_f32_e32 v32, 0xbfb8aa3b, v91
	v_exp_f32_e32 v32, v32
	s_nop 0
	v_add_f32_e32 v32, 1.0, v32
	v_rcp_f32_e32 v131, v32
	v_mul_f32_e32 v32, 0xbfb8aa3b, v83
	v_exp_f32_e32 v32, v32
	s_nop 0
	v_add_f32_e32 v32, 1.0, v32
	v_rcp_f32_e32 v153, v32
	v_mul_f32_e32 v32, 0xbfb8aa3b, v92
	v_exp_f32_e32 v32, v32
	s_nop 0
	v_add_f32_e32 v32, 1.0, v32
	v_rcp_f32_e32 v132, v32
	v_mul_f32_e32 v32, 0xbfb8aa3b, v84
	v_exp_f32_e32 v32, v32
	s_nop 0
	v_add_f32_e32 v32, 1.0, v32
	v_rcp_f32_e32 v154, v32
	v_mul_f32_e32 v32, 0xbfb8aa3b, v93
	v_exp_f32_e32 v32, v32
	s_nop 0
	v_add_f32_e32 v32, 1.0, v32
	v_rcp_f32_e32 v133, v32
	v_mul_f32_e32 v32, 0xbfb8aa3b, v85
	v_exp_f32_e32 v32, v32
	s_nop 0
	v_add_f32_e32 v32, 1.0, v32
	v_rcp_f32_e32 v155, v32
	v_or_b32_e32 v32, 48, v158
	v_mad_i64_i32 v[156:157], s[22:23], v32, s50, v[148:149]
	global_store_dwordx4 v[156:157], v[130:133], off
	global_store_dwordx4 v[156:157], v[152:155], off offset:16
	v_add_u32_e32 v32, 0x80, v158
	v_mul_f32_e32 v131, 0xbfb8aa3b, v58
	v_mul_f32_e32 v132, 0xbfb8aa3b, v59
	v_mul_f32_e32 v133, 0xbfb8aa3b, v60
	v_exp_f32_e32 v131, v131
	v_exp_f32_e32 v132, v132
	v_exp_f32_e32 v133, v133
	v_mul_f32_e32 v130, 0xbfb8aa3b, v62
	v_add_f32_e32 v131, 1.0, v131
	v_add_f32_e32 v132, 1.0, v132
	v_add_f32_e32 v133, 1.0, v133
	v_rcp_f32_e32 v152, v131
	v_mul_f32_e32 v131, 0xbfb8aa3b, v63
	v_rcp_f32_e32 v153, v132
	v_mul_f32_e32 v132, 0xbfb8aa3b, v64
	v_rcp_f32_e32 v154, v133
	v_mul_f32_e32 v133, 0xbfb8aa3b, v65
	v_exp_f32_e32 v130, v130
	v_exp_f32_e32 v131, v131
	v_exp_f32_e32 v132, v132
	v_exp_f32_e32 v133, v133
	v_mul_f32_e32 v155, 0xbfb8aa3b, v61
	v_exp_f32_e32 v155, v155
	v_mad_i64_i32 v[156:157], s[22:23], v32, s50, v[148:149]
	v_mul_f32_e32 v32, 0xbfb8aa3b, v54
	v_add_f32_e32 v130, 1.0, v130
	v_add_f32_e32 v131, 1.0, v131
	v_add_f32_e32 v132, 1.0, v132
	v_add_f32_e32 v133, 1.0, v133
	v_exp_f32_e32 v32, v32
	v_rcp_f32_e32 v130, v130
	v_rcp_f32_e32 v131, v131
	v_rcp_f32_e32 v132, v132
	v_rcp_f32_e32 v133, v133
	v_add_f32_e32 v155, 1.0, v155
	v_rcp_f32_e32 v155, v155
	v_add_f32_e32 v32, 1.0, v32
	global_store_dwordx4 v[156:157], v[130:133], off
	global_store_dwordx4 v[156:157], v[152:155], off offset:16
	s_nop 0
	v_rcp_f32_e32 v130, v32
	v_mul_f32_e32 v32, 0xbfb8aa3b, v50
	v_exp_f32_e32 v32, v32
	s_nop 0
	v_add_f32_e32 v32, 1.0, v32
	v_rcp_f32_e32 v152, v32
	v_mul_f32_e32 v32, 0xbfb8aa3b, v55
	v_exp_f32_e32 v32, v32
	s_nop 0
	v_add_f32_e32 v32, 1.0, v32
	v_rcp_f32_e32 v131, v32
	v_mul_f32_e32 v32, 0xbfb8aa3b, v51
	v_exp_f32_e32 v32, v32
	s_nop 0
	v_add_f32_e32 v32, 1.0, v32
	v_rcp_f32_e32 v153, v32
	v_mul_f32_e32 v32, 0xbfb8aa3b, v56
	v_exp_f32_e32 v32, v32
	s_nop 0
	v_add_f32_e32 v32, 1.0, v32
	v_rcp_f32_e32 v132, v32
	v_mul_f32_e32 v32, 0xbfb8aa3b, v52
	v_exp_f32_e32 v32, v32
	s_nop 0
	v_add_f32_e32 v32, 1.0, v32
	v_rcp_f32_e32 v154, v32
	v_mul_f32_e32 v32, 0xbfb8aa3b, v57
	v_exp_f32_e32 v32, v32
	s_nop 0
	v_add_f32_e32 v32, 1.0, v32
	v_rcp_f32_e32 v133, v32
	v_mul_f32_e32 v32, 0xbfb8aa3b, v53
	v_exp_f32_e32 v32, v32
	s_nop 0
	v_add_f32_e32 v32, 1.0, v32
	v_rcp_f32_e32 v155, v32
	v_add_u32_e32 v32, 0x90, v158
	v_mad_i64_i32 v[156:157], s[22:23], v32, s50, v[148:149]
	v_mul_f32_e32 v32, 0xbfb8aa3b, v42
	v_exp_f32_e32 v32, v32
	global_store_dwordx4 v[156:157], v[130:133], off
	global_store_dwordx4 v[156:157], v[152:155], off offset:16
	v_add_f32_e32 v32, 1.0, v32
	v_rcp_f32_e32 v130, v32
	v_mul_f32_e32 v32, 0xbfb8aa3b, v34
	v_exp_f32_e32 v32, v32
	s_nop 0
	v_add_f32_e32 v32, 1.0, v32
	v_rcp_f32_e32 v152, v32
	v_mul_f32_e32 v32, 0xbfb8aa3b, v43
	v_exp_f32_e32 v32, v32
	s_nop 0
	v_add_f32_e32 v32, 1.0, v32
	v_rcp_f32_e32 v131, v32
	v_mul_f32_e32 v32, 0xbfb8aa3b, v35
	v_exp_f32_e32 v32, v32
	s_nop 0
	v_add_f32_e32 v32, 1.0, v32
	v_rcp_f32_e32 v153, v32
	v_mul_f32_e32 v32, 0xbfb8aa3b, v44
	v_exp_f32_e32 v32, v32
	s_nop 0
	v_add_f32_e32 v32, 1.0, v32
	v_rcp_f32_e32 v132, v32
	v_mul_f32_e32 v32, 0xbfb8aa3b, v36
	v_exp_f32_e32 v32, v32
	s_nop 0
	v_add_f32_e32 v32, 1.0, v32
	v_rcp_f32_e32 v154, v32
	v_mul_f32_e32 v32, 0xbfb8aa3b, v45
	v_exp_f32_e32 v32, v32
	s_nop 0
	v_add_f32_e32 v32, 1.0, v32
	v_rcp_f32_e32 v133, v32
	v_mul_f32_e32 v32, 0xbfb8aa3b, v37
	v_exp_f32_e32 v32, v32
	s_nop 0
	v_add_f32_e32 v32, 1.0, v32
	v_rcp_f32_e32 v155, v32
	v_add_u32_e32 v32, 0xa0, v158
	v_mad_i64_i32 v[156:157], s[22:23], v32, s50, v[148:149]
	v_mul_f32_e32 v32, 0xbfb8aa3b, v24
	v_exp_f32_e32 v32, v32
	global_store_dwordx4 v[156:157], v[130:133], off
	global_store_dwordx4 v[156:157], v[152:155], off offset:16
	v_add_f32_e32 v32, 1.0, v32
	s_nop 0
	v_rcp_f32_e32 v152, v32
	v_mul_f32_e32 v32, 0xbfb8aa3b, v16
	v_exp_f32_e32 v32, v32
	s_nop 0
	v_add_f32_e32 v32, 1.0, v32
	v_rcp_f32_e32 v130, v32
	v_mul_f32_e32 v32, 0xbfb8aa3b, v25
	v_exp_f32_e32 v32, v32
	s_nop 0
	v_add_f32_e32 v32, 1.0, v32
	v_rcp_f32_e32 v153, v32
	v_mul_f32_e32 v32, 0xbfb8aa3b, v17
	v_exp_f32_e32 v32, v32
	s_nop 0
	v_add_f32_e32 v32, 1.0, v32
	v_rcp_f32_e32 v131, v32
	v_mul_f32_e32 v32, 0xbfb8aa3b, v26
	v_exp_f32_e32 v32, v32
	s_nop 0
	v_add_f32_e32 v32, 1.0, v32
	v_rcp_f32_e32 v154, v32
	v_mul_f32_e32 v32, 0xbfb8aa3b, v18
	v_exp_f32_e32 v32, v32
	s_nop 0
	v_add_f32_e32 v32, 1.0, v32
	v_rcp_f32_e32 v132, v32
	v_mul_f32_e32 v32, 0xbfb8aa3b, v27
	v_exp_f32_e32 v32, v32
	s_nop 0
	v_add_f32_e32 v32, 1.0, v32
	v_rcp_f32_e32 v155, v32
	v_mul_f32_e32 v32, 0xbfb8aa3b, v19
	v_exp_f32_e32 v32, v32
	s_nop 0
	v_add_f32_e32 v32, 1.0, v32
	v_rcp_f32_e32 v133, v32
	v_add_u32_e32 v32, 0xb0, v158
	v_mad_i64_i32 v[148:149], s[22:23], v32, s50, v[148:149]
	global_store_dwordx4 v[148:149], v[152:155], off
	s_mov_b64 s[22:23], exec
